# GLA vT staging: 24 odd/even exec-divergent merges replaced by v_perm_b32 with a per-lane selector, on top of v006
# speedup vs baseline: 1.0132x; 1.0132x over previous
; #define LAS __attribute__((address_space(3)))
; __device__ __forceinline__ unsigned xb_add(unsigned* p, unsigned v) { return __hip_atomic_fetch_add(p, v, __ATOMIC_RELAXED, __HIP_MEMORY_SCOPE_AGENT); }
; __device__ __forceinline__ unsigned xb_xcc_id() { return (unsigned)__builtin_amdgcn_s_getreg((3 << 11) | 20) & 0xFu; }
; __device__ __forceinline__ XcdBarrier xcd_barrier_post(unsigned* bar, volatile LAS unsigned* st) {
;     XcdBarrier b; b.bar = bar; b.x = xb_xcc_id(); b.st = st;
;     if (threadIdx.x == 0) (void)xb_add(&bar[XB_XCNT(b.x)], 1u);
;     return b;
; __global__ void __launch_bounds__(512, 2) fwd_kernel(Params p) {
;     extern __shared__ __attribute__((aligned(16))) unsigned char lds[];
;     cg::grid_group grid = cg::this_grid();
;     const int G = gridDim.x;
;     { volatile LAS unsigned* st0 = (volatile LAS unsigned*)((LAS unsigned char*)lds + 132096); if (threadIdx.x < 4) st0[threadIdx.x] = 0u; }
;     __syncthreads();
;     XcdBarrier bar = xcd_barrier_post((unsigned*)(p.ws + WS_BAR), (volatile LAS unsigned*)((LAS unsigned char*)lds + 132096));
_Z10fwd_kernel6Params:
	v_and_b32_e32 v147, 0x3ff, v0
	v_mbcnt_lo_u32_b32 v254, -1, 0
	v_mbcnt_hi_u32_b32 v254, -1, v254
	v_and_b32_e32 v254, 1, v254
	v_sub_u32_e32 v254, 0, v254
	v_and_b32_e32 v254, 0x6060606, v254
	v_xor_b32_e32 v254, 0x5040100, v254
	v_writelane_b32 v249, s2, 0
	s_load_dwordx16 s[12:27], s[0:1], 0x80
	s_load_dword s33, s[0:1], 0xc8
	s_load_dwordx2 s[2:3], s[0:1], 0xc0
	v_cmp_gt_u32_e32 vcc, 4, v147
	s_waitcnt lgkmcnt(0)
	v_writelane_b32 v249, s2, 1
	s_nop 1
	v_writelane_b32 v249, s3, 2
	s_add_u32 s2, s0, 0xc0
	s_addc_u32 s3, s1, 0
	s_and_saveexec_b64 s[4:5], vcc
	v_lshl_add_u32 v1, v147, 2, 0
	v_add_u32_e32 v1, 0x20400, v1
	v_mov_b32_e32 v2, 0
	ds_write_b32 v1, v2
	s_or_b64 exec, exec, s[4:5]
	s_waitcnt lgkmcnt(0)
	s_barrier
	s_getreg_b32 s4, hwreg(HW_REG_XCC_ID, 0, 4)
	s_and_b32 s40, s4, 15
	v_cmp_eq_u32_e64 s[6:7], 0, v147
	s_mov_b64 s[4:5], exec
	s_nop 0
	v_writelane_b32 v249, s6, 3
	s_nop 1
	v_writelane_b32 v249, s7, 4
	s_and_b64 s[6:7], s[4:5], s[6:7]
	s_mov_b64 exec, s[6:7]
	s_cbranch_execz .LBB0_5
	s_mov_b64 s[6:7], exec
	v_mbcnt_lo_u32_b32 v1, s6, 0
	v_mbcnt_hi_u32_b32 v1, s7, v1
	v_cmp_eq_u32_e32 vcc, 0, v1
	s_and_b64 s[8:9], exec, vcc
	s_mov_b64 exec, s[8:9]
	s_cbranch_execz .LBB0_5
	s_lshl_b32 s8, s40, 8
	s_bcnt1_i32_b64 s6, s[6:7]
	v_mov_b32_e32 v1, s8
	v_mov_b32_e32 v2, s6
	global_atomic_add v1, v2, s[26:27] offset:1024

; __device__ __forceinline__ unsigned pk2(float lo, float hi) { const f32x2_t v = {lo, hi}; return __builtin_bit_cast(unsigned, __builtin_convertvector(v, bf16x2_t)); }
; __device__ __forceinline__ f32x2 ex2v(f32x2 x) { f32x2 r; r.x = __builtin_amdgcn_exp2f(x.x); r.y = __builtin_amdgcn_exp2f(x.y); return r; }
; template <int DKH, int DVW>
; __device__ __forceinline__ void gla_chain(const Params& p, int jl, unsigned char* lds, int seq, int h, int e, int dk0, int dv0, bf16_t* OUTB, int ostride, int orow_off) {
;     ...
;             for (int s = 0; s < NSEG; ++s) { const f32x2 sv = *(const f32x2*)(segtot + s * DKH + 2 * dkp); tot += sv; const bool inc = e == 0 ? (s < seg) : (s > seg); off += inc ? sv : (f32x2){0.f, 0.f}; }
;             const f32x2 dec = ex2v(tot);
;             if (seg == 0) *(f32x2*)(decs + 2 * dkp) = dec;
;             f32x2 ke[NP];
; #pragma unroll
;             for (int i = 0; i < NP; ++i) { const f32x2 b = bl[i] + off; const f32x2 eb = ex2v(b), enb = ex2v(-b);
;                 const f32x2 qf = (f32x2){__uint_as_float(qraw[i] << 16), __uint_as_float(qraw[i] & 0xffff0000u)} * QSCALE * eb;
;                 const f32x2 kf = (f32x2){__uint_as_float(kraw[i] << 16), __uint_as_float(kraw[i] & 0xffff0000u)} * enb;
;                 *(unsigned*)(qd + (seg * NP + i) * 272 + dkp * 4) = pk2(qf.x, qf.y);
;                 *(unsigned*)(kd + (seg * NP + i) * 272 + dkp * 4) = pk2(kf.x, kf.y);
;                 ke[i] = kf * dec; }
.LBB0_256:
	v_cndmask_b32_e64 v117, 0, v117, s[42:43]
	v_cndmask_b32_e64 v116, 0, v116, s[42:43]
	v_cndmask_b32_e64 v101, 0, v101, s[44:45]
	v_cndmask_b32_e64 v100, 0, v100, s[44:45]
	v_pk_add_f32 v[100:101], v[116:117], v[100:101]
	v_cndmask_b32_e64 v95, 0, v95, s[46:47]
	v_cndmask_b32_e64 v94, 0, v94, s[46:47]
	v_pk_add_f32 v[94:95], v[100:101], v[94:95]
	v_cndmask_b32_e64 v97, 0, v97, s[48:49]
	v_cndmask_b32_e64 v96, 0, v96, s[48:49]
	v_pk_add_f32 v[94:95], v[94:95], v[96:97]
	v_cndmask_b32_e64 v91, 0, v91, s[50:51]
	v_cndmask_b32_e64 v90, 0, v90, s[50:51]
	v_pk_add_f32 v[90:91], v[94:95], v[90:91]
	v_cndmask_b32_e64 v93, 0, v93, s[52:53]
	v_cndmask_b32_e64 v92, 0, v92, s[52:53]
	v_pk_add_f32 v[90:91], v[90:91], v[92:93]
	v_cndmask_b32_e64 v87, 0, v87, s[54:55]
	v_cndmask_b32_e64 v86, 0, v86, s[54:55]
	v_pk_add_f32 v[86:87], v[90:91], v[86:87]
	v_cndmask_b32_e64 v89, 0, v89, s[56:57]
	v_cndmask_b32_e64 v88, 0, v88, s[56:57]
	v_pk_add_f32 v[86:87], v[86:87], v[88:89]
	s_waitcnt vmcnt(19)
	v_lshlrev_b32_e32 v92, 16, v182
	v_pk_add_f32 v[88:89], v[128:129], v[86:87]
	v_and_b32_e32 v93, 0xffff0000, v182
	v_exp_f32_e32 v90, v88
	v_exp_f32_e32 v91, v89
	v_exp_f32_e64 v88, -v88
	v_exp_f32_e64 v89, -v89
	v_pk_mul_f32 v[92:93], v[92:93], s[28:29] op_sel_hi:[1,0]
	s_waitcnt vmcnt(17)
	v_lshlrev_b32_e32 v94, 16, v180
	v_pk_mul_f32 v[90:91], v[92:93], v[90:91]
	v_lshlrev_b32_e32 v92, 16, v181
	v_and_b32_e32 v93, 0xffff0000, v181
	v_pk_mul_f32 v[88:89], v[88:89], v[92:93]
	v_cvt_pk_bf16_f32 v0, v90, v91
	v_cvt_pk_bf16_f32 v96, v88, v89
	v_pk_mul_f32 v[90:91], v[98:99], v[88:89]
	v_pk_add_f32 v[88:89], v[114:115], v[86:87]
	v_and_b32_e32 v95, 0xffff0000, v180
	v_exp_f32_e32 v92, v88
	v_exp_f32_e32 v93, v89
	v_exp_f32_e64 v88, -v88
	v_exp_f32_e64 v89, -v89
	v_pk_mul_f32 v[94:95], v[94:95], s[28:29] op_sel_hi:[1,0]
	v_add_u32_e32 v116, s11, v156
	v_pk_mul_f32 v[92:93], v[94:95], v[92:93]
	s_waitcnt vmcnt(16)
	v_lshlrev_b32_e32 v94, 16, v179
	v_and_b32_e32 v95, 0xffff0000, v179
	v_pk_mul_f32 v[88:89], v[88:89], v[94:95]
	v_cvt_pk_bf16_f32 v92, v92, v93
	v_add_u32_e32 v114, 0x3400, v116
	ds_write2_b32 v114, v0, v92 offset1:68
	v_cvt_pk_bf16_f32 v0, v88, v89
	v_pk_mul_f32 v[92:93], v[98:99], v[88:89]
	v_pk_add_f32 v[88:89], v[112:113], v[86:87]
	v_add_u32_e32 v115, 0x7800, v116
	v_exp_f32_e32 v94, v88
	v_exp_f32_e32 v95, v89
	v_exp_f32_e64 v88, -v88
	v_exp_f32_e64 v89, -v89
	ds_write2_b32 v115, v96, v0 offset1:68
	s_waitcnt vmcnt(15)
	v_lshlrev_b32_e32 v96, 16, v178
	v_and_b32_e32 v97, 0xffff0000, v178
	v_pk_mul_f32 v[96:97], v[96:97], s[28:29] op_sel_hi:[1,0]
	s_waitcnt vmcnt(13)
	v_lshlrev_b32_e32 v100, 16, v175
	v_pk_mul_f32 v[94:95], v[96:97], v[94:95]
	v_lshlrev_b32_e32 v96, 16, v177
	v_and_b32_e32 v97, 0xffff0000, v177
	v_pk_mul_f32 v[88:89], v[88:89], v[96:97]
	v_cvt_pk_bf16_f32 v0, v94, v95
	v_cvt_pk_bf16_f32 v112, v88, v89
	v_pk_mul_f32 v[94:95], v[98:99], v[88:89]
	v_pk_add_f32 v[88:89], v[110:111], v[86:87]
	v_and_b32_e32 v101, 0xffff0000, v175
	v_exp_f32_e32 v96, v88
	v_exp_f32_e32 v97, v89
	v_exp_f32_e64 v88, -v88
	v_exp_f32_e64 v89, -v89
	v_pk_mul_f32 v[100:101], v[100:101], s[28:29] op_sel_hi:[1,0]
	v_add_u32_e32 v111, 0x3800, v116
	v_pk_mul_f32 v[96:97], v[100:101], v[96:97]
	s_waitcnt vmcnt(12)
	v_lshlrev_b32_e32 v100, 16, v173
	v_and_b32_e32 v101, 0xffff0000, v173
	v_pk_mul_f32 v[88:89], v[88:89], v[100:101]
	v_cvt_pk_bf16_f32 v96, v96, v97
	ds_write2_b32 v114, v0, v96 offset0:136 offset1:204
	v_cvt_pk_bf16_f32 v0, v88, v89
	v_pk_mul_f32 v[96:97], v[98:99], v[88:89]
	v_pk_add_f32 v[88:89], v[108:109], v[86:87]
	s_waitcnt vmcnt(11)
	v_lshlrev_b32_e32 v108, 16, v176
	v_exp_f32_e32 v100, v88
	v_exp_f32_e32 v101, v89
	v_exp_f32_e64 v88, -v88
	v_exp_f32_e64 v89, -v89
	v_and_b32_e32 v109, 0xffff0000, v176
	v_pk_mul_f32 v[108:109], v[108:109], s[28:29] op_sel_hi:[1,0]
	ds_write2_b32 v115, v112, v0 offset0:136 offset1:204
	v_pk_mul_f32 v[100:101], v[108:109], v[100:101]
	s_waitcnt vmcnt(10)
	v_lshlrev_b32_e32 v108, 16, v174
	v_and_b32_e32 v109, 0xffff0000, v174
	v_pk_mul_f32 v[88:89], v[88:89], v[108:109]
	v_cvt_pk_bf16_f32 v0, v100, v101
	v_cvt_pk_bf16_f32 v110, v88, v89
	v_pk_mul_f32 v[100:101], v[98:99], v[88:89]
	v_pk_add_f32 v[88:89], v[106:107], v[86:87]
	s_waitcnt vmcnt(9)
	v_lshlrev_b32_e32 v108, 16, v172
	v_exp_f32_e32 v106, v88
	v_exp_f32_e32 v107, v89
	v_exp_f32_e64 v88, -v88
	v_exp_f32_e64 v89, -v89
	v_and_b32_e32 v109, 0xffff0000, v172
	v_pk_mul_f32 v[108:109], v[108:109], s[28:29] op_sel_hi:[1,0]
	v_add_u32_e32 v112, 0x7c00, v116
	v_pk_mul_f32 v[106:107], v[108:109], v[106:107]
	s_waitcnt vmcnt(8)
	v_lshlrev_b32_e32 v108, 16, v171
	v_and_b32_e32 v109, 0xffff0000, v171
	v_pk_mul_f32 v[88:89], v[88:89], v[108:109]
	v_cvt_pk_bf16_f32 v106, v106, v107
	ds_write2_b32 v111, v0, v106 offset0:16 offset1:84
	v_cvt_pk_bf16_f32 v0, v88, v89
	v_pk_mul_f32 v[106:107], v[98:99], v[88:89]
	v_pk_add_f32 v[88:89], v[104:105], v[86:87]
	s_waitcnt vmcnt(7)
	v_lshlrev_b32_e32 v108, 16, v170
	v_exp_f32_e32 v104, v88
	v_exp_f32_e32 v105, v89
	v_exp_f32_e64 v88, -v88
	v_exp_f32_e64 v89, -v89
	v_and_b32_e32 v109, 0xffff0000, v170
	v_pk_mul_f32 v[108:109], v[108:109], s[28:29] op_sel_hi:[1,0]
	v_pk_add_f32 v[86:87], v[102:103], v[86:87]
	v_pk_mul_f32 v[104:105], v[108:109], v[104:105]
	s_waitcnt vmcnt(6)
	v_lshlrev_b32_e32 v108, 16, v169
	v_and_b32_e32 v109, 0xffff0000, v169
	v_pk_mul_f32 v[88:89], v[88:89], v[108:109]
	ds_write2_b32 v112, v110, v0 offset0:16 offset1:84
	v_cvt_pk_bf16_f32 v0, v104, v105
	v_cvt_pk_bf16_f32 v108, v88, v89
	v_pk_mul_f32 v[104:105], v[98:99], v[88:89]
	v_exp_f32_e32 v88, v86
	v_exp_f32_e32 v89, v87
	v_exp_f32_e64 v86, -v86
	v_exp_f32_e64 v87, -v87
	s_waitcnt vmcnt(5)
; template <int DKH, int DVW>
; __device__ __forceinline__ void gla_chain(const Params& p, int jl, unsigned char* lds, int seq, int h, int e, int dk0, int dv0, bf16_t* OUTB, int ostride, int orow_off) {
;     ...
;                 ke[i] = kf * dec; }
;             if constexpr (NP == 8) { u32x4 w0, w1; w0.x = pk2(ke[0].x, ke[1].x); w0.y = pk2(ke[2].x, ke[3].x); w0.z = pk2(ke[4].x, ke[5].x); w0.w = pk2(ke[6].x, ke[7].x);
;               w1.x = pk2(ke[0].y, ke[1].y); w1.y = pk2(ke[2].y, ke[3].y); w1.z = pk2(ke[4].y, ke[5].y); w1.w = pk2(ke[6].y, ke[7].y);
;               *(u32x4*)(keT + (2 * dkp) * 144 + seg * 16) = w0; *(u32x4*)(keT + (2 * dkp + 1) * 144 + seg * 16) = w1; }
;             else { u32x2 w0, w1; w0.x = pk2(ke[0].x, ke[1].x); w0.y = pk2(ke[2].x, ke[3].x); w1.x = pk2(ke[0].y, ke[1].y); w1.y = pk2(ke[2].y, ke[3].y);
;               *(u32x2*)(keT + (2 * dkp) * 144 + seg * 8) = w0; *(u32x2*)(keT + (2 * dkp + 1) * 144 + seg * 8) = w1; }
; #pragma unroll
;             for (int jv = 0; jv < NV; ++jv) { const unsigned wd[4] = {vraw[jv].x, vraw[jv].y, vraw[jv].z, vraw[jv].w};
; #pragma unroll
;                 for (int k2 = 0; k2 < 4; ++k2) { const unsigned r = wd[k2], q = (unsigned)__builtin_amdgcn_mov_dpp((int)r, 0xB1, 0xf, 0xf, true);
;                     const bool odd = (lane & 1) != 0;
;                     const unsigned word = odd ? ((q >> 16) | (r & 0xffff0000u)) : ((r & 0xffffu) | (q << 16));
;                     *(unsigned*)(vTw + (jv * 8 + 2 * k2 + (odd ? 1 : 0)) * 144 + (lane >> 1) * 4) = word; } }
;             LDS_BARRIER();
;             { const int st = wave >> 1, ct0 = (wave & 1) * 2;
;               bf16x8 Af[KS], Bf[2][KS];
; #pragma unroll
;               for (int ks = 0; ks < KS; ++ks) { Af[ks] = *(const bf16x8*)(kd + (st * 16 + fr) * 272 + (ks * 32 + fq * 8) * 2);
;                   Bf[0][ks] = *(const bf16x8*)(qd + (ct0 * 16 + fr) * 272 + (ks * 32 + fq * 8) * 2); Bf[1][ks] = *(const bf16x8*)(qd + ((ct0 + 1) * 16 + fr) * 272 + (ks * 32 + fq * 8) * 2); }
;               __builtin_amdgcn_sched_barrier(0);
;               f32x4 a0 = (f32x4){0.f, 0.f, 0.f, 0.f}, a1 = a0;
; #pragma unroll
;               for (int ks = 0; ks < KS; ++ks) { a0 = __builtin_amdgcn_mfma_f32_16x16x32_bf16(Af[ks], Bf[0][ks], a0, 0, 0, 0); a1 = __builtin_amdgcn_mfma_f32_16x16x32_bf16(Af[ks], Bf[1][ks], a1, 0, 0, 0); }
;               const int sb = st * 16 + fq * 4;
	v_lshlrev_b32_e32 v102, 16, v168
	v_and_b32_e32 v103, 0xffff0000, v168
	v_pk_mul_f32 v[102:103], v[102:103], s[28:29] op_sel_hi:[1,0]
	s_nop 0
	v_pk_mul_f32 v[88:89], v[102:103], v[88:89]
	s_waitcnt vmcnt(4)
	v_lshlrev_b32_e32 v102, 16, v167
	v_and_b32_e32 v103, 0xffff0000, v167
	v_pk_mul_f32 v[86:87], v[86:87], v[102:103]
	v_cvt_pk_bf16_f32 v88, v88, v89
	v_pk_mul_f32 v[98:99], v[98:99], v[86:87]
	ds_write2_b32 v111, v0, v88 offset0:152 offset1:220
	v_cvt_pk_bf16_f32 v0, v86, v87
	v_cvt_pk_bf16_f32 v86, v90, v92
	v_cvt_pk_bf16_f32 v87, v94, v96
	v_cvt_pk_bf16_f32 v88, v100, v106
	v_cvt_pk_bf16_f32 v89, v104, v98
	ds_write2_b32 v112, v108, v0 offset0:152 offset1:220
	v_cvt_pk_bf16_f32 v90, v91, v93
	v_cvt_pk_bf16_f32 v91, v95, v97
	v_cvt_pk_bf16_f32 v92, v101, v107
	v_cvt_pk_bf16_f32 v93, v105, v99
	ds_write_b128 v158, v[86:89] offset:48128
	ds_write_b128 v158, v[90:93] offset:48272
	s_waitcnt vmcnt(0)
	v_mov_b32_dpp v86, v82 quad_perm:[1,0,3,2] row_mask:0xf bank_mask:0xf bound_ctrl:1
	v_perm_b32 v0, v86, v82, v254
	v_mov_b32_dpp v82, v83 quad_perm:[1,0,3,2] row_mask:0xf bank_mask:0xf bound_ctrl:1
	ds_write_b32 v166, v0
	v_perm_b32 v0, v82, v83, v254
	v_mov_b32_dpp v82, v84 quad_perm:[1,0,3,2] row_mask:0xf bank_mask:0xf bound_ctrl:1
	ds_write_b32 v166, v0 offset:288
	v_perm_b32 v0, v82, v84, v254
	v_mov_b32_dpp v82, v85 quad_perm:[1,0,3,2] row_mask:0xf bank_mask:0xf bound_ctrl:1
	ds_write_b32 v166, v0 offset:576
	v_perm_b32 v0, v82, v85, v254
	v_mov_b32_dpp v82, v78 quad_perm:[1,0,3,2] row_mask:0xf bank_mask:0xf bound_ctrl:1
	ds_write_b32 v166, v0 offset:864
	v_perm_b32 v0, v82, v78, v254
	v_mov_b32_dpp v78, v79 quad_perm:[1,0,3,2] row_mask:0xf bank_mask:0xf bound_ctrl:1
	ds_write_b32 v166, v0 offset:1152
	v_perm_b32 v0, v78, v79, v254
	v_mov_b32_dpp v78, v80 quad_perm:[1,0,3,2] row_mask:0xf bank_mask:0xf bound_ctrl:1
	ds_write_b32 v166, v0 offset:1440
	v_perm_b32 v0, v78, v80, v254
	v_mov_b32_dpp v78, v81 quad_perm:[1,0,3,2] row_mask:0xf bank_mask:0xf bound_ctrl:1
	ds_write_b32 v166, v0 offset:1728
	v_perm_b32 v0, v78, v81, v254
	v_mov_b32_dpp v78, v74 quad_perm:[1,0,3,2] row_mask:0xf bank_mask:0xf bound_ctrl:1
	ds_write_b32 v166, v0 offset:2016
	v_perm_b32 v0, v78, v74, v254
	v_mov_b32_dpp v74, v75 quad_perm:[1,0,3,2] row_mask:0xf bank_mask:0xf bound_ctrl:1
	ds_write_b32 v166, v0 offset:2304
	v_perm_b32 v0, v74, v75, v254
	v_mov_b32_dpp v74, v76 quad_perm:[1,0,3,2] row_mask:0xf bank_mask:0xf bound_ctrl:1
	ds_write_b32 v166, v0 offset:2592
	v_perm_b32 v0, v74, v76, v254
	v_mov_b32_dpp v74, v77 quad_perm:[1,0,3,2] row_mask:0xf bank_mask:0xf bound_ctrl:1
	ds_write_b32 v166, v0 offset:2880
	v_perm_b32 v0, v74, v77, v254
	v_mov_b32_dpp v74, v70 quad_perm:[1,0,3,2] row_mask:0xf bank_mask:0xf bound_ctrl:1
	ds_write_b32 v166, v0 offset:3168
	v_perm_b32 v0, v74, v70, v254
	v_mov_b32_dpp v70, v71 quad_perm:[1,0,3,2] row_mask:0xf bank_mask:0xf bound_ctrl:1
	ds_write_b32 v166, v0 offset:3456
	v_perm_b32 v0, v70, v71, v254
	v_mov_b32_dpp v70, v72 quad_perm:[1,0,3,2] row_mask:0xf bank_mask:0xf bound_ctrl:1
	ds_write_b32 v166, v0 offset:3744
	v_perm_b32 v0, v70, v72, v254
	v_mov_b32_dpp v70, v73 quad_perm:[1,0,3,2] row_mask:0xf bank_mask:0xf bound_ctrl:1
	ds_write_b32 v166, v0 offset:4032
	v_perm_b32 v0, v70, v73, v254
	ds_write_b32 v166, v0 offset:4320
	s_waitcnt lgkmcnt(0)
	s_barrier
	ds_read_b128 v[70:73], v159 offset:30720
	ds_read_b128 v[74:77], v159 offset:30784
	ds_read_b128 v[78:81], v160 offset:13312
	ds_read_b128 v[82:85], v160 offset:13376
	ds_read_b128 v[86:89], v160 offset:17664
	ds_read_b128 v[90:93], v160 offset:17728
	ds_read_b128 v[94:97], v159 offset:30848
	ds_read_b128 v[98:101], v159 offset:30912
	ds_read_b128 v[102:105], v160 offset:13440
	ds_read_b128 v[106:109], v160 offset:13504
	ds_read_b128 v[110:113], v160 offset:17792
	ds_read_b128 v[114:117], v160 offset:17856
	s_waitcnt lgkmcnt(9)
	v_mfma_f32_16x16x32_bf16 v[78:81], v[70:73], v[78:81], 0
	v_add_u32_e32 v167, 0x4000, v164
	v_add_u32_e32 v200, 0x5000, v164
	v_add_u32_e32 v201, 0x6000, v164
	s_waitcnt lgkmcnt(7)
	v_mfma_f32_16x16x32_bf16 v[70:73], v[70:73], v[86:89], 0
	v_cvt_pk_bf16_f32 v128, v6, v7
	v_cvt_pk_bf16_f32 v129, v8, v9
	v_cvt_pk_bf16_f32 v130, v14, v15
	v_mfma_f32_16x16x32_bf16 v[78:81], v[74:77], v[82:85], v[78:81]
	v_cvt_pk_bf16_f32 v131, v16, v17
	v_cvt_pk_bf16_f32 v132, v10, v11
	v_cvt_pk_bf16_f32 v133, v12, v13
	s_waitcnt lgkmcnt(6)
	v_mfma_f32_16x16x32_bf16 v[70:73], v[74:77], v[90:93], v[70:73]
	v_cvt_pk_bf16_f32 v134, v18, v19
	v_cvt_pk_bf16_f32 v135, v20, v21
	v_cvt_pk_bf16_f32 v136, v22, v23
	s_waitcnt lgkmcnt(3)
	v_mfma_f32_16x16x32_bf16 v[78:81], v[94:97], v[102:105], v[78:81]
	v_cvt_pk_bf16_f32 v137, v24, v25
	v_cvt_pk_bf16_f32 v138, v30, v31
	v_cvt_pk_bf16_f32 v139, v32, v33
	s_waitcnt lgkmcnt(1)
	v_mfma_f32_16x16x32_bf16 v[70:73], v[94:97], v[110:113], v[70:73]
	v_cvt_pk_bf16_f32 v168, v26, v27
	v_cvt_pk_bf16_f32 v169, v28, v29
	v_cvt_pk_bf16_f32 v170, v34, v35
	v_mfma_f32_16x16x32_bf16 v[78:81], v[98:101], v[106:109], v[78:81]
	v_cvt_pk_bf16_f32 v171, v36, v37
	v_cvt_pk_bf16_f32 v172, v38, v39
	v_cvt_pk_bf16_f32 v173, v40, v41
	s_waitcnt lgkmcnt(0)
	v_mfma_f32_16x16x32_bf16 v[70:73], v[98:101], v[114:117], v[70:73]
	v_cvt_pk_bf16_f32 v174, v46, v47
	s_nop 1
	v_cndmask_b32_e64 v0, 0, v78, s[58:59]
	v_cndmask_b32_e64 v74, 0, v79, s[60:61]
	v_cndmask_b32_e64 v75, 0, v80, s[62:63]
	v_cndmask_b32_e64 v76, 0, v81, s[64:65]
	v_cvt_pk_bf16_f32 v74, v0, v74
	v_cndmask_b32_e64 v0, 0, v70, s[66:67]
	v_cndmask_b32_e64 v70, 0, v71, s[68:69]
	v_cndmask_b32_e64 v71, 0, v72, s[70:71]
	v_cndmask_b32_e64 v72, 0, v73, s[72:73]
	v_cvt_pk_bf16_f32 v75, v75, v76
	v_cvt_pk_bf16_f32 v70, v0, v70
	v_cvt_pk_bf16_f32 v71, v71, v72
	ds_write_b64 v161, v[74:75]
	ds_write_b64 v161, v[70:71] offset:2304
	s_waitcnt lgkmcnt(0)
	s_barrier
; template <int DKH, int DVW>
; __device__ __forceinline__ void gla_chain(const Params& p, int jl, unsigned char* lds, int seq, int h, int e, int dk0, int dv0, bf16_t* OUTB, int ostride, int orow_off) {
;     ...
;             bf16x8 vf[DT][2];
; #pragma unroll
;             for (int dt = 0; dt < DT; ++dt)
; #pragma unroll
;                 for (int ks = 0; ks < 2; ++ks) vf[dt][ks] = *(const bf16x8*)(vTw + (dt * 16 + fr) * 144 + (ks * 32 + fq * 8) * 2);
;             f32x4 o[DT][4];
;             { bf16x8 Bs[2][4];
; #pragma unroll
;               for (int ks = 0; ks < 2; ++ks)
; #pragma unroll
;                   for (int ct = 0; ct < 4; ++ct) Bs[ks][ct] = *(const bf16x8*)(sc + (ct * 16 + fr) * 144 + (ks * 32 + fq * 8) * 2);
;               bf16x8 Sbf[KS][DT];
; #pragma unroll
;               for (int ks = 0; ks < KS; ++ks)
; #pragma unroll
;                   for (int dt = 0; dt < DT; ++dt) { const f32x4 x0 = Sacc[2 * ks][dt], x1 = Sacc[2 * ks + 1][dt];
;                       const u32x4 w = (u32x4){pk2(x0[0], x0[1]), pk2(x0[2], x0[3]), pk2(x1[0], x1[1]), pk2(x1[2], x1[3])}; Sbf[ks][dt] = __builtin_bit_cast(bf16x8, w); }
;               u32x4 Bq[2][4];
;     ...
;               GLA_LDQ(0, 0);
;               __builtin_amdgcn_sched_barrier(0);
; #pragma unroll
;               for (int ct = 0; ct < 4; ++ct)
; #pragma unroll
;                   for (int dt = 0; dt < DT; ++dt) o[dt][ct] = __builtin_amdgcn_mfma_f32_16x16x32_bf16(vf[dt][0], Bs[0][ct], (f32x4){0.f, 0.f, 0.f, 0.f}, 0, 0, 0);
; #pragma unroll
;               for (int ct = 0; ct < 4; ++ct)
; #pragma unroll
;                   for (int dt = 0; dt < DT; ++dt) o[dt][ct] = __builtin_amdgcn_mfma_f32_16x16x32_bf16(vf[dt][1], Bs[1][ct], o[dt][ct], 0, 0, 0);
; #pragma unroll
;               for (int ks = 0; ks < KS; ++ks) {
;                   if (ks < KS - 1) GLA_LDQ((ks + 1) & 1, ks + 1);
;                   __builtin_amdgcn_sched_barrier(0);
; #pragma unroll
;                   for (int ct = 0; ct < 4; ++ct) { const bf16x8 B = __builtin_bit_cast(bf16x8, Bq[ks & 1][ct]);
; #pragma unroll
;                       for (int dt = 0; dt < DT; ++dt) o[dt][ct] = __builtin_amdgcn_mfma_f32_16x16x32_bf16(Sbf[ks][dt], B, o[dt][ct], 0, 0, 0); }
;                   __builtin_amdgcn_sched_barrier(0);
;               }
	ds_read_b128 v[82:85], v162
	ds_read_b128 v[70:73], v162 offset:64
	ds_read_b128 v[78:81], v162 offset:2304
	ds_read_b128 v[74:77], v162 offset:2368
	ds_read_b128 v[86:89], v163
	ds_read_b128 v[90:93], v163 offset:64
	ds_read_b128 v[94:97], v163 offset:2304
	ds_read_b128 v[98:101], v163 offset:2368
	ds_read_b128 v[102:105], v163 offset:4608
	ds_read_b128 v[106:109], v163 offset:4672
	ds_read_b128 v[110:113], v163 offset:6912
	ds_read_b128 v[114:117], v163 offset:6976
	v_add_u32_e32 v0, 0x3000, v164
	ds_read2_b64 v[184:187], v0 offset0:128 offset1:132
	ds_read2_b64 v[188:191], v167 offset0:160 offset1:164
	ds_read2_b64 v[192:195], v200 offset0:192 offset1:196
	ds_read2_b64 v[196:199], v201 offset0:224 offset1:228
	v_cvt_pk_bf16_f32 v175, v48, v49
	v_cvt_pk_bf16_f32 v176, v42, v43
	v_cvt_pk_bf16_f32 v177, v44, v45
	v_cvt_pk_bf16_f32 v178, v50, v51
	v_cvt_pk_bf16_f32 v179, v52, v53
	v_cvt_pk_bf16_f32 v180, v54, v55
	v_cvt_pk_bf16_f32 v181, v56, v57
	v_cvt_pk_bf16_f32 v182, v62, v63
	v_cvt_pk_bf16_f32 v183, v64, v65
	v_cvt_pk_bf16_f32 v214, v58, v59
	v_cvt_pk_bf16_f32 v215, v60, v61
	v_cvt_pk_bf16_f32 v216, v66, v67
	v_cvt_pk_bf16_f32 v217, v68, v69
	s_waitcnt lgkmcnt(11)
	v_mfma_f32_16x16x32_bf16 v[218:221], v[82:85], v[86:89], 0
	v_mfma_f32_16x16x32_bf16 v[86:89], v[78:81], v[86:89], 0
	s_waitcnt lgkmcnt(9)
	v_mfma_f32_16x16x32_bf16 v[222:225], v[82:85], v[94:97], 0
	v_mfma_f32_16x16x32_bf16 v[94:97], v[78:81], v[94:97], 0
	s_waitcnt lgkmcnt(7)
	v_mfma_f32_16x16x32_bf16 v[226:229], v[82:85], v[102:105], 0
	v_mfma_f32_16x16x32_bf16 v[102:105], v[78:81], v[102:105], 0
	s_waitcnt lgkmcnt(5)
	v_mfma_f32_16x16x32_bf16 v[230:233], v[82:85], v[110:113], 0
	v_mfma_f32_16x16x32_bf16 v[110:113], v[78:81], v[110:113], 0
	v_mfma_f32_16x16x32_bf16 v[218:221], v[70:73], v[90:93], v[218:221]
	v_mfma_f32_16x16x32_bf16 v[86:89], v[74:77], v[90:93], v[86:89]
	v_mfma_f32_16x16x32_bf16 v[90:93], v[70:73], v[98:101], v[222:225]
	v_mfma_f32_16x16x32_bf16 v[94:97], v[74:77], v[98:101], v[94:97]
	v_mfma_f32_16x16x32_bf16 v[98:101], v[70:73], v[106:109], v[226:229]
	v_mfma_f32_16x16x32_bf16 v[102:105], v[74:77], v[106:109], v[102:105]
	s_waitcnt lgkmcnt(4)
	v_mfma_f32_16x16x32_bf16 v[106:109], v[70:73], v[114:117], v[230:233]
	v_mfma_f32_16x16x32_bf16 v[110:113], v[74:77], v[114:117], v[110:113]
	ds_read2_b64 v[114:117], v0 offset0:136 offset1:140
	ds_read2_b64 v[222:225], v167 offset0:168 offset1:172
	ds_read2_b64 v[226:229], v200 offset0:200 offset1:204
	ds_read2_b64 v[230:233], v201 offset0:232 offset1:236
	s_waitcnt lgkmcnt(7)
	v_mfma_f32_16x16x32_bf16 v[218:221], v[128:131], v[184:187], v[218:221]
	v_mfma_f32_16x16x32_bf16 v[86:89], v[132:135], v[184:187], v[86:89]
	s_waitcnt lgkmcnt(6)
	v_mfma_f32_16x16x32_bf16 v[90:93], v[128:131], v[188:191], v[90:93]
	v_mfma_f32_16x16x32_bf16 v[94:97], v[132:135], v[188:191], v[94:97]
	s_waitcnt lgkmcnt(5)
	v_mfma_f32_16x16x32_bf16 v[98:101], v[128:131], v[192:195], v[98:101]
	v_mfma_f32_16x16x32_bf16 v[102:105], v[132:135], v[192:195], v[102:105]
	s_waitcnt lgkmcnt(4)
	v_mfma_f32_16x16x32_bf16 v[106:109], v[128:131], v[196:199], v[106:109]
	v_mfma_f32_16x16x32_bf16 v[110:113], v[132:135], v[196:199], v[110:113]
	ds_read2_b64 v[128:131], v0 offset0:144 offset1:148
	ds_read2_b64 v[132:135], v167 offset0:176 offset1:180
	ds_read2_b64 v[184:187], v200 offset0:208 offset1:212
	ds_read2_b64 v[188:191], v201 offset0:240 offset1:244
	s_waitcnt lgkmcnt(7)
	v_mfma_f32_16x16x32_bf16 v[192:195], v[136:139], v[114:117], v[218:221]
	v_mfma_f32_16x16x32_bf16 v[86:89], v[168:171], v[114:117], v[86:89]
	s_waitcnt lgkmcnt(6)
	v_mfma_f32_16x16x32_bf16 v[90:93], v[136:139], v[222:225], v[90:93]
	v_mfma_f32_16x16x32_bf16 v[94:97], v[168:171], v[222:225], v[94:97]
	s_waitcnt lgkmcnt(5)
	v_mfma_f32_16x16x32_bf16 v[98:101], v[136:139], v[226:229], v[98:101]
	v_mfma_f32_16x16x32_bf16 v[102:105], v[168:171], v[226:229], v[102:105]
	s_waitcnt lgkmcnt(4)
	v_mfma_f32_16x16x32_bf16 v[106:109], v[136:139], v[230:233], v[106:109]
	v_mfma_f32_16x16x32_bf16 v[110:113], v[168:171], v[230:233], v[110:113]
	ds_read2_b64 v[114:117], v0 offset0:152 offset1:156
	ds_read2_b64 v[136:139], v167 offset0:184 offset1:188
	ds_read2_b64 v[168:171], v200 offset0:216 offset1:220
	ds_read2_b64 v[196:199], v201 offset0:248 offset1:252
	s_waitcnt lgkmcnt(7)
	v_mfma_f32_16x16x32_bf16 v[192:195], v[172:175], v[128:131], v[192:195]
	v_mfma_f32_16x16x32_bf16 v[86:89], v[176:179], v[128:131], v[86:89]
	s_waitcnt lgkmcnt(6)
	v_mfma_f32_16x16x32_bf16 v[90:93], v[172:175], v[132:135], v[90:93]
	v_mfma_f32_16x16x32_bf16 v[94:97], v[176:179], v[132:135], v[94:97]
	s_waitcnt lgkmcnt(5)
	v_mfma_f32_16x16x32_bf16 v[98:101], v[172:175], v[184:187], v[98:101]
	v_mfma_f32_16x16x32_bf16 v[102:105], v[176:179], v[184:187], v[102:105]
	s_waitcnt lgkmcnt(4)
	v_mfma_f32_16x16x32_bf16 v[106:109], v[172:175], v[188:191], v[106:109]
	v_mfma_f32_16x16x32_bf16 v[110:113], v[176:179], v[188:191], v[110:113]
	s_waitcnt lgkmcnt(3)
	v_mfma_f32_16x16x32_bf16 v[128:131], v[180:183], v[114:117], v[192:195]
	v_mfma_f32_16x16x32_bf16 v[86:89], v[214:217], v[114:117], v[86:89]
	s_waitcnt lgkmcnt(2)
	v_mfma_f32_16x16x32_bf16 v[90:93], v[180:183], v[136:139], v[90:93]
	v_mfma_f32_16x16x32_bf16 v[94:97], v[214:217], v[136:139], v[94:97]
	s_waitcnt lgkmcnt(1)
	v_mfma_f32_16x16x32_bf16 v[98:101], v[180:183], v[168:171], v[98:101]
	v_mfma_f32_16x16x32_bf16 v[102:105], v[214:217], v[168:171], v[102:105]
	s_waitcnt lgkmcnt(0)
; __device__ __forceinline__ unsigned pk2(float lo, float hi) { const f32x2_t v = {lo, hi}; return __builtin_bit_cast(unsigned, __builtin_convertvector(v, bf16x2_t)); }
; #define GLA_LDK(buf, g_) do { _Pragma("unroll") for (int d2 = 0; d2 < 2; ++d2) { dcv[buf][d2] = *(const f32x4*)(decs + ((g_) * 2 + d2) * 16 + fq * 4); \
;                   _Pragma("unroll") for (int ks = 0; ks < 2; ++ks) Ak[buf][d2][ks] = *(const bf16x8*)(keT + (((g_) * 2 + d2) * 16 + fr) * 144 + (ks * 32 + fq * 8) * 2); } } while (0)
; template <int DKH, int DVW>
; __device__ __forceinline__ void gla_chain(const Params& p, int jl, unsigned char* lds, int seq, int h, int e, int dk0, int dv0, bf16_t* OUTB, int ostride, int orow_off) {
;     ...
; #pragma unroll
;             for (int ct = 0; ct < 4; ++ct)
; #pragma unroll
;                 for (int dt = 0; dt < DT; ++dt) { u32x2 w; w.x = pk2(o[dt][ct][0], o[dt][ct][1]); w.y = pk2(o[dt][ct][2], o[dt][ct][3]);
;                     *(u32x2*)(OUTB + (size_t)(tokc0 - orow_off + ct * 16 + fr) * ostride + h * 256 + dv0 + wave * DVW + dt * 16 + fq * 4) = w; }
;             { bf16x8 Ak[2][2][2]; f32x4 dcv[2][2];
;     ...
;               GLA_LDK(0, 0);
; #pragma unroll
;               for (int g = 0; g < DKT / 2; ++g) {
;                   if (g < DKT / 2 - 1) GLA_LDK((g + 1) & 1, g + 1);
;                   __builtin_amdgcn_sched_barrier(0);
; #pragma unroll
;                   for (int d2 = 0; d2 < 2; ++d2) { const int dkt = g * 2 + d2;
; #pragma unroll
;                       for (int dt = 0; dt < DT; ++dt) Sacc[dkt][dt] *= dcv[g & 1][d2];
; #pragma unroll
;                       for (int ks = 0; ks < 2; ++ks)
; #pragma unroll
;                           for (int dt = 0; dt < DT; ++dt) Sacc[dkt][dt] = __builtin_amdgcn_mfma_f32_16x16x32_bf16(Ak[g & 1][d2][ks], vf[dt][ks], Sacc[dkt][dt], 0, 0, 0); }
;                   __builtin_amdgcn_sched_barrier(0);
;               }
;     ...
;             }
;             if (tid < 256 && n + 1 < nch) *(f32x4*)(g1nxt + gc * 16 + gr4 * 4) = g1n;
	v_mfma_f32_16x16x32_bf16 v[106:109], v[180:183], v[196:199], v[106:109]
	v_mfma_f32_16x16x32_bf16 v[110:113], v[214:217], v[196:199], v[110:113]
	v_or_b32_e32 v0, s82, v141
	v_lshlrev_b32_e32 v0, 10, v0
	v_lshl_add_u64 v[114:115], v[0:1], 1, v[126:127]
	v_cvt_pk_bf16_f32 v86, v86, v87
	v_cvt_pk_bf16_f32 v87, v88, v89
	global_store_dwordx2 v[114:115], v[86:87], off offset:32
	v_ashrrev_i32_e32 v87, 31, v0
	v_mov_b32_e32 v86, v0
	v_lshl_add_u64 v[86:87], v[86:87], 1, v[126:127]
	s_mov_b32 s2, 0x8000
	v_cvt_pk_bf16_f32 v88, v90, v91
	v_add_co_u32_e32 v90, vcc, s2, v86
	v_cvt_pk_bf16_f32 v89, v92, v93
	s_nop 0
	v_addc_co_u32_e32 v91, vcc, 0, v87, vcc
	global_store_dwordx2 v[90:91], v[88:89], off
	v_cvt_pk_bf16_f32 v88, v94, v95
	v_cvt_pk_bf16_f32 v89, v96, v97
	s_mov_b32 s2, 0x10000
	global_store_dwordx2 v[90:91], v[88:89], off offset:32
	v_add_co_u32_e32 v90, vcc, s2, v86
	v_cvt_pk_bf16_f32 v88, v98, v99
	v_cvt_pk_bf16_f32 v89, v100, v101
	v_addc_co_u32_e32 v91, vcc, 0, v87, vcc
	s_mov_b32 s2, 0x18000
	global_store_dwordx2 v[90:91], v[88:89], off
	v_cvt_pk_bf16_f32 v88, v102, v103
	v_cvt_pk_bf16_f32 v89, v104, v105
	v_add_co_u32_e32 v86, vcc, s2, v86
	global_store_dwordx2 v[90:91], v[88:89], off offset:32
	v_cvt_pk_bf16_f32 v88, v106, v107
	v_cvt_pk_bf16_f32 v89, v108, v109
	v_addc_co_u32_e32 v87, vcc, 0, v87, vcc
	v_cvt_pk_bf16_f32 v116, v128, v129
	v_cvt_pk_bf16_f32 v117, v130, v131
	global_store_dwordx2 v[86:87], v[88:89], off
	v_cvt_pk_bf16_f32 v88, v110, v111
	v_cvt_pk_bf16_f32 v89, v112, v113
	global_store_dwordx2 v[114:115], v[116:117], off
	global_store_dwordx2 v[86:87], v[88:89], off offset:32
	v_add_u32_e32 v0, v157, v124
	ds_read_b128 v[86:89], v0 offset:12288
	ds_read_b128 v[90:93], v165 offset:48128
	ds_read_b128 v[94:97], v165 offset:48192
	ds_read_b128 v[98:101], v0 offset:12352
	ds_read_b128 v[102:105], v165 offset:50432
	ds_read_b128 v[106:109], v165 offset:50496
	ds_read_b128 v[110:113], v0 offset:12416
	ds_read_b128 v[114:117], v165 offset:52736
	ds_read_b128 v[128:131], v165 offset:52800
	ds_read_b128 v[132:135], v0 offset:12480
	ds_read_b128 v[136:139], v165 offset:55040
	ds_read_b128 v[168:171], v165 offset:55104
	s_waitcnt lgkmcnt(11)
	v_pk_mul_f32 v[6:7], v[6:7], v[86:87]
	v_pk_mul_f32 v[8:9], v[8:9], v[88:89]
	v_pk_mul_f32 v[10:11], v[10:11], v[86:87]
	v_pk_mul_f32 v[12:13], v[12:13], v[88:89]
	s_waitcnt lgkmcnt(8)
	v_pk_mul_f32 v[14:15], v[14:15], v[98:99]
	v_pk_mul_f32 v[16:17], v[16:17], v[100:101]
	v_pk_mul_f32 v[18:19], v[18:19], v[98:99]
	v_pk_mul_f32 v[20:21], v[20:21], v[100:101]
	v_mfma_f32_16x16x32_bf16 v[6:9], v[90:93], v[82:85], v[6:9]
	v_mfma_f32_16x16x32_bf16 v[10:13], v[90:93], v[78:81], v[10:13]
	s_waitcnt lgkmcnt(7)
	v_mfma_f32_16x16x32_bf16 v[14:17], v[102:105], v[82:85], v[14:17]
	v_mfma_f32_16x16x32_bf16 v[18:21], v[102:105], v[78:81], v[18:21]
	v_mfma_f32_16x16x32_bf16 v[6:9], v[94:97], v[70:73], v[6:9]
	v_mfma_f32_16x16x32_bf16 v[10:13], v[94:97], v[74:77], v[10:13]
	s_waitcnt lgkmcnt(6)
	v_mfma_f32_16x16x32_bf16 v[14:17], v[106:109], v[70:73], v[14:17]
	v_mfma_f32_16x16x32_bf16 v[18:21], v[106:109], v[74:77], v[18:21]
	ds_read_b128 v[86:89], v165 offset:57344
	ds_read_b128 v[90:93], v165 offset:57408
	ds_read_b128 v[94:97], v0 offset:12544
	ds_read_b128 v[98:101], v0 offset:12608
	ds_read_b128 v[102:105], v165 offset:59648
	ds_read_b128 v[106:109], v165 offset:59712
	s_waitcnt lgkmcnt(11)
	v_pk_mul_f32 v[22:23], v[22:23], v[110:111]
	v_pk_mul_f32 v[24:25], v[24:25], v[112:113]
	v_pk_mul_f32 v[26:27], v[26:27], v[110:111]
	v_pk_mul_f32 v[28:29], v[28:29], v[112:113]
	s_waitcnt lgkmcnt(8)
	v_pk_mul_f32 v[30:31], v[30:31], v[132:133]
	v_pk_mul_f32 v[32:33], v[32:33], v[134:135]
	v_pk_mul_f32 v[34:35], v[34:35], v[132:133]
	v_pk_mul_f32 v[36:37], v[36:37], v[134:135]
	v_mfma_f32_16x16x32_bf16 v[22:25], v[114:117], v[82:85], v[22:25]
	v_mfma_f32_16x16x32_bf16 v[26:29], v[114:117], v[78:81], v[26:29]
	s_waitcnt lgkmcnt(7)
	v_mfma_f32_16x16x32_bf16 v[30:33], v[136:139], v[82:85], v[30:33]
	v_mfma_f32_16x16x32_bf16 v[34:37], v[136:139], v[78:81], v[34:37]
	v_mfma_f32_16x16x32_bf16 v[22:25], v[128:131], v[70:73], v[22:25]
	v_mfma_f32_16x16x32_bf16 v[26:29], v[128:131], v[74:77], v[26:29]
	s_waitcnt lgkmcnt(6)
	v_mfma_f32_16x16x32_bf16 v[30:33], v[168:171], v[70:73], v[30:33]
	v_mfma_f32_16x16x32_bf16 v[34:37], v[168:171], v[74:77], v[34:37]
	ds_read_b128 v[110:113], v165 offset:61952
	ds_read_b128 v[114:117], v165 offset:62016
	ds_read_b128 v[128:131], v0 offset:12672
	ds_read_b128 v[132:135], v0 offset:12736
	ds_read_b128 v[136:139], v165 offset:64256
	ds_read_b128 v[168:171], v165 offset:64320
	s_waitcnt lgkmcnt(9)
	v_pk_mul_f32 v[38:39], v[38:39], v[94:95]
	v_pk_mul_f32 v[40:41], v[40:41], v[96:97]
	v_pk_mul_f32 v[42:43], v[42:43], v[94:95]
	v_pk_mul_f32 v[44:45], v[44:45], v[96:97]
	s_waitcnt lgkmcnt(8)
	v_pk_mul_f32 v[46:47], v[46:47], v[98:99]
	v_pk_mul_f32 v[48:49], v[48:49], v[100:101]
	v_pk_mul_f32 v[50:51], v[50:51], v[98:99]
	v_pk_mul_f32 v[52:53], v[52:53], v[100:101]
	v_mfma_f32_16x16x32_bf16 v[38:41], v[86:89], v[82:85], v[38:41]
	v_mfma_f32_16x16x32_bf16 v[42:45], v[86:89], v[78:81], v[42:45]
	s_waitcnt lgkmcnt(7)
	v_mfma_f32_16x16x32_bf16 v[46:49], v[102:105], v[82:85], v[46:49]
	v_mfma_f32_16x16x32_bf16 v[50:53], v[102:105], v[78:81], v[50:53]
	v_mfma_f32_16x16x32_bf16 v[38:41], v[90:93], v[70:73], v[38:41]
	v_mfma_f32_16x16x32_bf16 v[42:45], v[90:93], v[74:77], v[42:45]
	s_waitcnt lgkmcnt(6)
	v_mfma_f32_16x16x32_bf16 v[46:49], v[106:109], v[70:73], v[46:49]
	v_mfma_f32_16x16x32_bf16 v[50:53], v[106:109], v[74:77], v[50:53]
	s_waitcnt lgkmcnt(3)
	v_pk_mul_f32 v[54:55], v[54:55], v[128:129]
	v_pk_mul_f32 v[56:57], v[56:57], v[130:131]
	v_pk_mul_f32 v[58:59], v[58:59], v[128:129]
	v_pk_mul_f32 v[60:61], v[60:61], v[130:131]
	s_waitcnt lgkmcnt(2)
	v_pk_mul_f32 v[62:63], v[62:63], v[132:133]
	v_pk_mul_f32 v[64:65], v[64:65], v[134:135]
	v_pk_mul_f32 v[66:67], v[66:67], v[132:133]
	v_pk_mul_f32 v[68:69], v[68:69], v[134:135]
	v_mfma_f32_16x16x32_bf16 v[54:57], v[110:113], v[82:85], v[54:57]
	v_mfma_f32_16x16x32_bf16 v[58:61], v[110:113], v[78:81], v[58:61]
	s_waitcnt lgkmcnt(1)
	v_mfma_f32_16x16x32_bf16 v[62:65], v[136:139], v[82:85], v[62:65]
	v_mfma_f32_16x16x32_bf16 v[66:69], v[136:139], v[78:81], v[66:69]
	v_mfma_f32_16x16x32_bf16 v[54:57], v[114:117], v[70:73], v[54:57]
	v_mfma_f32_16x16x32_bf16 v[58:61], v[114:117], v[74:77], v[58:61]
	s_waitcnt lgkmcnt(0)
	v_mfma_f32_16x16x32_bf16 v[62:65], v[168:171], v[70:73], v[62:65]
	v_mfma_f32_16x16x32_bf16 v[66:69], v[168:171], v[74:77], v[66:69]
	s_and_saveexec_b64 s[2:3], s[80:81]
	s_cbranch_execz .LBB0_246
	s_and_b32 s5, s75, 0x400
	v_lshl_add_u32 v0, s5, 2, v125
	ds_write_b128 v0, v[2:5]
	s_branch .LBB0_246

; __device__ __forceinline__ unsigned pk2(float lo, float hi) { const f32x2_t v = {lo, hi}; return __builtin_bit_cast(unsigned, __builtin_convertvector(v, bf16x2_t)); }
; #define LDS_BARRIER() do { asm volatile("s_waitcnt lgkmcnt(0)" ::: "memory"); __builtin_amdgcn_s_barrier(); asm volatile("" ::: "memory"); } while (0)
; __device__ __forceinline__ f32x2 ex2v(f32x2 x) { f32x2 r; r.x = __builtin_amdgcn_exp2f(x.x); r.y = __builtin_amdgcn_exp2f(x.y); return r; }
; template <int DKH, int DVW>
; __device__ __forceinline__ void gla_chain(const Params& p, int jl, unsigned char* lds, int seq, int h, int e, int dk0, int dv0, bf16_t* OUTB, int ostride, int orow_off) {
;     ...
;             LDS_BARRIER();
;             f32x2 off = (f32x2){0.f, 0.f}, tot = (f32x2){0.f, 0.f};
; #pragma unroll
;             for (int s = 0; s < NSEG; ++s) { const f32x2 sv = *(const f32x2*)(segtot + s * DKH + 2 * dkp); tot += sv; const bool inc = e == 0 ? (s < seg) : (s > seg); off += inc ? sv : (f32x2){0.f, 0.f}; }
;             const f32x2 dec = ex2v(tot);
;             if (seg == 0) *(f32x2*)(decs + 2 * dkp) = dec;
;             f32x2 ke[NP];
; #pragma unroll
;             for (int i = 0; i < NP; ++i) { const f32x2 b = bl[i] + off; const f32x2 eb = ex2v(b), enb = ex2v(-b);
;                 const f32x2 qf = (f32x2){__uint_as_float(qraw[i] << 16), __uint_as_float(qraw[i] & 0xffff0000u)} * QSCALE * eb;
;                 const f32x2 kf = (f32x2){__uint_as_float(kraw[i] << 16), __uint_as_float(kraw[i] & 0xffff0000u)} * enb;
;                 *(unsigned*)(qd + (seg * NP + i) * 272 + dkp * 4) = pk2(qf.x, qf.y);
;                 *(unsigned*)(kd + (seg * NP + i) * 272 + dkp * 4) = pk2(kf.x, kf.y);
;                 ke[i] = kf * dec; }
.LBB0_347:
	ds_write_b64 v84, v[34:35] offset:8192
	s_waitcnt lgkmcnt(0)
	s_barrier
	v_add_u32_e32 v32, 0x2000, v86
	ds_read2_b64 v[58:61], v32 offset1:32
	ds_read2_b64 v[54:57], v32 offset0:64 offset1:96
	ds_read2_b64 v[50:53], v32 offset0:128 offset1:160
	ds_read2_b64 v[46:49], v32 offset0:192 offset1:224
	v_add_u32_e32 v32, 0x2800, v86
	s_waitcnt lgkmcnt(3)
	v_pk_add_f32 v[78:79], v[58:59], 0 op_sel_hi:[1,0]
	ds_read2_b64 v[42:45], v32 offset1:32
	v_pk_add_f32 v[30:31], v[78:79], v[60:61]
	ds_read2_b64 v[38:41], v32 offset0:64 offset1:96
	s_waitcnt lgkmcnt(4)
	v_pk_add_f32 v[30:31], v[30:31], v[54:55]
	ds_read2_b64 v[34:37], v32 offset0:128 offset1:160
	v_pk_add_f32 v[30:31], v[30:31], v[56:57]
	s_waitcnt lgkmcnt(4)
	v_pk_add_f32 v[30:31], v[30:31], v[50:51]
	s_nop 0
	v_pk_add_f32 v[30:31], v[30:31], v[52:53]
	s_waitcnt lgkmcnt(3)
	v_pk_add_f32 v[30:31], v[30:31], v[46:47]
	s_nop 0
	v_pk_add_f32 v[30:31], v[30:31], v[48:49]
	s_waitcnt lgkmcnt(2)
	v_pk_add_f32 v[30:31], v[30:31], v[42:43]
	s_nop 0
	v_pk_add_f32 v[58:59], v[30:31], v[44:45]
	ds_read2_b64 v[30:33], v32 offset0:192 offset1:224
	s_waitcnt lgkmcnt(2)
	v_pk_add_f32 v[58:59], v[58:59], v[38:39]
	s_nop 0
	v_pk_add_f32 v[58:59], v[58:59], v[40:41]
	s_waitcnt lgkmcnt(1)
	v_pk_add_f32 v[58:59], v[58:59], v[34:35]
	s_nop 0
	v_pk_add_f32 v[58:59], v[58:59], v[36:37]
	s_waitcnt lgkmcnt(0)
	v_pk_add_f32 v[58:59], v[58:59], v[30:31]
	s_nop 0
	v_pk_add_f32 v[58:59], v[58:59], v[32:33]
	s_nop 0
	v_exp_f32_e32 v58, v58
	v_exp_f32_e32 v59, v59
	s_and_saveexec_b64 s[90:91], s[36:37]
	ds_write_b64 v86, v[58:59] offset:12288
	s_or_b64 exec, exec, s[90:91]
	v_cndmask_b32_e64 v79, 0, v79, s[40:41]
	v_cndmask_b32_e64 v78, 0, v78, s[40:41]
	v_cndmask_b32_e64 v61, 0, v61, s[42:43]
	v_cndmask_b32_e64 v60, 0, v60, s[42:43]
	v_pk_add_f32 v[60:61], v[78:79], v[60:61]
	v_cndmask_b32_e64 v55, 0, v55, s[44:45]
	v_cndmask_b32_e64 v54, 0, v54, s[44:45]
	v_pk_add_f32 v[54:55], v[60:61], v[54:55]
	v_cndmask_b32_e64 v57, 0, v57, s[46:47]
	v_cndmask_b32_e64 v56, 0, v56, s[46:47]
	v_pk_add_f32 v[54:55], v[54:55], v[56:57]
	v_cndmask_b32_e64 v51, 0, v51, s[48:49]
	v_cndmask_b32_e64 v50, 0, v50, s[48:49]
	v_pk_add_f32 v[50:51], v[54:55], v[50:51]
	v_cndmask_b32_e64 v53, 0, v53, s[50:51]
	v_cndmask_b32_e64 v52, 0, v52, s[50:51]
	v_pk_add_f32 v[50:51], v[50:51], v[52:53]
	v_cndmask_b32_e64 v47, 0, v47, s[52:53]
	v_cndmask_b32_e64 v46, 0, v46, s[52:53]
	v_pk_add_f32 v[46:47], v[50:51], v[46:47]
	v_cndmask_b32_e64 v49, 0, v49, s[54:55]
	v_cndmask_b32_e64 v48, 0, v48, s[54:55]
	v_pk_add_f32 v[46:47], v[46:47], v[48:49]
	v_cndmask_b32_e64 v43, 0, v43, s[56:57]
	v_cndmask_b32_e64 v42, 0, v42, s[56:57]
	v_pk_add_f32 v[42:43], v[46:47], v[42:43]
	v_cndmask_b32_e64 v45, 0, v45, s[58:59]
	v_cndmask_b32_e64 v44, 0, v44, s[58:59]
	v_pk_add_f32 v[42:43], v[42:43], v[44:45]
	v_cndmask_b32_e64 v39, 0, v39, s[60:61]
	v_cndmask_b32_e64 v38, 0, v38, s[60:61]
	v_pk_add_f32 v[38:39], v[42:43], v[38:39]
	v_cndmask_b32_e64 v41, 0, v41, s[62:63]
	v_cndmask_b32_e64 v40, 0, v40, s[62:63]
	v_pk_add_f32 v[38:39], v[38:39], v[40:41]
	v_cndmask_b32_e64 v35, 0, v35, s[64:65]
	v_cndmask_b32_e64 v34, 0, v34, s[64:65]
	v_pk_add_f32 v[34:35], v[38:39], v[34:35]
	v_cndmask_b32_e64 v37, 0, v37, s[84:85]
	v_cndmask_b32_e64 v36, 0, v36, s[84:85]
	v_pk_add_f32 v[34:35], v[34:35], v[36:37]
	v_cndmask_b32_e64 v31, 0, v31, s[86:87]
	v_cndmask_b32_e64 v30, 0, v30, s[86:87]
	v_pk_add_f32 v[30:31], v[34:35], v[30:31]
	v_cndmask_b32_e64 v33, 0, v33, s[88:89]
	v_cndmask_b32_e64 v32, 0, v32, s[88:89]
	v_pk_add_f32 v[30:31], v[30:31], v[32:33]
	s_waitcnt vmcnt(9)
	v_lshlrev_b32_e32 v36, 16, v109
	v_pk_add_f32 v[32:33], v[70:71], v[30:31]
	v_and_b32_e32 v37, 0xffff0000, v109
	v_exp_f32_e32 v34, v32
	v_exp_f32_e32 v35, v33
	v_exp_f32_e64 v32, -v32
	v_exp_f32_e64 v33, -v33
	v_pk_mul_f32 v[36:37], v[36:37], s[28:29] op_sel_hi:[1,0]
	s_waitcnt vmcnt(7)
	v_lshlrev_b32_e32 v38, 16, v107
	v_pk_mul_f32 v[34:35], v[36:37], v[34:35]
	v_lshlrev_b32_e32 v36, 16, v108
	v_and_b32_e32 v37, 0xffff0000, v108
	v_cvt_pk_bf16_f32 v40, v34, v35
	v_pk_add_f32 v[34:35], v[76:77], v[30:31]
	v_pk_mul_f32 v[32:33], v[32:33], v[36:37]
	v_exp_f32_e32 v36, v34
	v_exp_f32_e32 v37, v35
	v_exp_f32_e64 v34, -v34
	v_exp_f32_e64 v35, -v35
	v_and_b32_e32 v39, 0xffff0000, v107
	v_pk_mul_f32 v[38:39], v[38:39], s[28:29] op_sel_hi:[1,0]
	v_add_u32_e32 v42, 0x3400, v94
	v_pk_mul_f32 v[36:37], v[38:39], v[36:37]
	s_waitcnt vmcnt(6)
	v_lshlrev_b32_e32 v38, 16, v106
	v_and_b32_e32 v39, 0xffff0000, v106
	v_pk_mul_f32 v[34:35], v[34:35], v[38:39]
	v_cvt_pk_bf16_f32 v36, v36, v37
	v_cvt_pk_bf16_f32 v41, v32, v33
	ds_write2_b32 v42, v40, v36 offset1:68
	v_cvt_pk_bf16_f32 v36, v34, v35
	v_add_u32_e32 v43, 0x7800, v94
	ds_write2_b32 v43, v41, v36 offset1:68
	v_pk_add_f32 v[36:37], v[74:75], v[30:31]
	s_waitcnt vmcnt(5)
	v_lshlrev_b32_e32 v40, 16, v105
	v_exp_f32_e32 v38, v36
	v_exp_f32_e32 v39, v37
	v_and_b32_e32 v41, 0xffff0000, v105
	v_exp_f32_e64 v36, -v36
	v_exp_f32_e64 v37, -v37
	v_pk_mul_f32 v[40:41], v[40:41], s[28:29] op_sel_hi:[1,0]
	v_pk_add_f32 v[30:31], v[72:73], v[30:31]
	v_pk_mul_f32 v[38:39], v[40:41], v[38:39]
	s_waitcnt vmcnt(4)
	v_lshlrev_b32_e32 v40, 16, v104
	v_cvt_pk_bf16_f32 v44, v38, v39
	v_exp_f32_e32 v38, v30
	v_exp_f32_e32 v39, v31
	v_and_b32_e32 v41, 0xffff0000, v104
	v_exp_f32_e64 v30, -v30
	v_exp_f32_e64 v31, -v31
	v_pk_mul_f32 v[36:37], v[36:37], v[40:41]
	s_waitcnt vmcnt(3)
	v_lshlrev_b32_e32 v40, 16, v103
	v_and_b32_e32 v41, 0xffff0000, v103
	v_pk_mul_f32 v[40:41], v[40:41], s[28:29] op_sel_hi:[1,0]
	v_pk_mul_f32 v[32:33], v[58:59], v[32:33]
	v_pk_mul_f32 v[38:39], v[40:41], v[38:39]
	s_waitcnt vmcnt(2)
; template <int DKH, int DVW>
; __device__ __forceinline__ void gla_chain(const Params& p, int jl, unsigned char* lds, int seq, int h, int e, int dk0, int dv0, bf16_t* OUTB, int ostride, int orow_off) {
;     ...
;             if constexpr (NP == 8) { u32x4 w0, w1; w0.x = pk2(ke[0].x, ke[1].x); w0.y = pk2(ke[2].x, ke[3].x); w0.z = pk2(ke[4].x, ke[5].x); w0.w = pk2(ke[6].x, ke[7].x);
;               w1.x = pk2(ke[0].y, ke[1].y); w1.y = pk2(ke[2].y, ke[3].y); w1.z = pk2(ke[4].y, ke[5].y); w1.w = pk2(ke[6].y, ke[7].y);
;               *(u32x4*)(keT + (2 * dkp) * 144 + seg * 16) = w0; *(u32x4*)(keT + (2 * dkp + 1) * 144 + seg * 16) = w1; }
;             else { u32x2 w0, w1; w0.x = pk2(ke[0].x, ke[1].x); w0.y = pk2(ke[2].x, ke[3].x); w1.x = pk2(ke[0].y, ke[1].y); w1.y = pk2(ke[2].y, ke[3].y);
;               *(u32x2*)(keT + (2 * dkp) * 144 + seg * 8) = w0; *(u32x2*)(keT + (2 * dkp + 1) * 144 + seg * 8) = w1; }
; #pragma unroll
;             for (int jv = 0; jv < NV; ++jv) { const unsigned wd[4] = {vraw[jv].x, vraw[jv].y, vraw[jv].z, vraw[jv].w};
; #pragma unroll
;                 for (int k2 = 0; k2 < 4; ++k2) { const unsigned r = wd[k2], q = (unsigned)__builtin_amdgcn_mov_dpp((int)r, 0xB1, 0xf, 0xf, true);
;                     const bool odd = (lane & 1) != 0;
;                     const unsigned word = odd ? ((q >> 16) | (r & 0xffff0000u)) : ((r & 0xffffu) | (q << 16));
;                     *(unsigned*)(vTw + (jv * 8 + 2 * k2 + (odd ? 1 : 0)) * 144 + (lane >> 1) * 4) = word; } }
;             LDS_BARRIER();
;             { const int st = wave >> 1, ct0 = (wave & 1) * 2;
;               bf16x8 Af[KS], Bf[2][KS];
; #pragma unroll
;               for (int ks = 0; ks < KS; ++ks) { Af[ks] = *(const bf16x8*)(kd + (st * 16 + fr) * 272 + (ks * 32 + fq * 8) * 2);
;                   Bf[0][ks] = *(const bf16x8*)(qd + (ct0 * 16 + fr) * 272 + (ks * 32 + fq * 8) * 2); Bf[1][ks] = *(const bf16x8*)(qd + ((ct0 + 1) * 16 + fr) * 272 + (ks * 32 + fq * 8) * 2); }
;               __builtin_amdgcn_sched_barrier(0);
;               f32x4 a0 = (f32x4){0.f, 0.f, 0.f, 0.f}, a1 = a0;
; #pragma unroll
;               for (int ks = 0; ks < KS; ++ks) { a0 = __builtin_amdgcn_mfma_f32_16x16x32_bf16(Af[ks], Bf[0][ks], a0, 0, 0, 0); a1 = __builtin_amdgcn_mfma_f32_16x16x32_bf16(Af[ks], Bf[1][ks], a1, 0, 0, 0); }
;               const int sb = st * 16 + fq * 4;
; #pragma unroll
	v_lshlrev_b32_e32 v40, 16, v102
	v_and_b32_e32 v41, 0xffff0000, v102
	v_pk_mul_f32 v[30:31], v[30:31], v[40:41]
	v_cvt_pk_bf16_f32 v38, v38, v39
	v_pk_mul_f32 v[34:35], v[58:59], v[34:35]
	v_cvt_pk_bf16_f32 v45, v36, v37
	v_pk_mul_f32 v[36:37], v[58:59], v[36:37]
	ds_write2_b32 v42, v44, v38 offset0:136 offset1:204
	v_cvt_pk_bf16_f32 v38, v30, v31
	v_pk_mul_f32 v[30:31], v[58:59], v[30:31]
	ds_write2_b32 v43, v45, v38 offset0:136 offset1:204
	v_cvt_pk_bf16_f32 v38, v32, v34
	v_cvt_pk_bf16_f32 v39, v36, v30
	v_cvt_pk_bf16_f32 v30, v33, v35
	v_cvt_pk_bf16_f32 v31, v37, v31
	ds_write2_b64 v100, v[38:39], v[30:31] offset0:128 offset1:146
	s_waitcnt vmcnt(0)
	v_mov_b32_dpp v31, v26 quad_perm:[1,0,3,2] row_mask:0xf bank_mask:0xf bound_ctrl:1
	v_perm_b32 v30, v31, v26, v254
	ds_write_b32 v101, v30
	v_mov_b32_dpp v30, v27 quad_perm:[1,0,3,2] row_mask:0xf bank_mask:0xf bound_ctrl:1
	v_perm_b32 v26, v30, v27, v254
	v_mov_b32_dpp v27, v28 quad_perm:[1,0,3,2] row_mask:0xf bank_mask:0xf bound_ctrl:1
	ds_write_b32 v101, v26 offset:288
	v_perm_b32 v26, v27, v28, v254
	ds_write_b32 v101, v26 offset:576
	v_mov_b32_dpp v26, v29 quad_perm:[1,0,3,2] row_mask:0xf bank_mask:0xf bound_ctrl:1
	v_perm_b32 v30, v26, v29, v254
	v_mov_b32_dpp v27, v22 quad_perm:[1,0,3,2] row_mask:0xf bank_mask:0xf bound_ctrl:1
	ds_write_b32 v101, v30 offset:864
	v_perm_b32 v26, v27, v22, v254
	ds_write_b32 v101, v26 offset:1152
	v_mov_b32_dpp v26, v23 quad_perm:[1,0,3,2] row_mask:0xf bank_mask:0xf bound_ctrl:1
	v_perm_b32 v22, v26, v23, v254
	v_mov_b32_dpp v23, v24 quad_perm:[1,0,3,2] row_mask:0xf bank_mask:0xf bound_ctrl:1
	ds_write_b32 v101, v22 offset:1440
	v_perm_b32 v22, v23, v24, v254
	ds_write_b32 v101, v22 offset:1728
	v_mov_b32_dpp v22, v25 quad_perm:[1,0,3,2] row_mask:0xf bank_mask:0xf bound_ctrl:1
	v_perm_b32 v26, v22, v25, v254
	ds_write_b32 v101, v26 offset:2016
	s_waitcnt lgkmcnt(0)
	s_barrier
	ds_read_b128 v[22:25], v95 offset:30720
	ds_read_b128 v[26:29], v95 offset:30784
	ds_read_b128 v[30:33], v96 offset:13312
	ds_read_b128 v[34:37], v96 offset:13376
	ds_read_b128 v[38:41], v96 offset:17664
	ds_read_b128 v[42:45], v96 offset:17728
	s_waitcnt lgkmcnt(3)
	v_mfma_f32_16x16x32_bf16 v[30:33], v[22:25], v[30:33], 0
	v_add_u32_e32 v58, v88, v93
	v_add_u32_e32 v78, 0x3000, v99
	v_add_u32_e32 v79, 0x4000, v99
	s_waitcnt lgkmcnt(1)
	v_mfma_f32_16x16x32_bf16 v[22:25], v[22:25], v[38:41], 0
	v_add_u32_e32 v118, 0x5000, v99
	v_add_u32_e32 v119, 0x6000, v99
	v_cvt_pk_bf16_f32 v70, v6, v7
	v_mfma_f32_16x16x32_bf16 v[30:33], v[26:29], v[34:37], v[30:33]
	v_add_u32_e32 v34, v88, v87
	v_cvt_pk_bf16_f32 v71, v8, v9
	v_cvt_pk_bf16_f32 v72, v10, v11
	s_waitcnt lgkmcnt(0)
	v_mfma_f32_16x16x32_bf16 v[22:25], v[26:29], v[42:45], v[22:25]
	v_cvt_pk_bf16_f32 v73, v12, v13
	s_nop 1
	v_cndmask_b32_e64 v30, 0, v30, s[66:67]
	v_cndmask_b32_e64 v31, 0, v31, s[68:69]
	v_cndmask_b32_e64 v32, 0, v32, s[70:71]
	v_cndmask_b32_e64 v33, 0, v33, s[72:73]
	s_nop 0
	v_cndmask_b32_e64 v22, 0, v22, s[76:77]
	v_cndmask_b32_e64 v23, 0, v23, s[78:79]
	v_cndmask_b32_e64 v24, 0, v24, s[80:81]
	v_cndmask_b32_e64 v25, 0, v25, s[82:83]
	v_cvt_pk_bf16_f32 v30, v30, v31
	v_cvt_pk_bf16_f32 v31, v32, v33
	v_cvt_pk_bf16_f32 v22, v22, v23
	v_cvt_pk_bf16_f32 v23, v24, v25
	ds_write_b64 v97, v[30:31]
	ds_write_b64 v97, v[22:23] offset:2304
	s_waitcnt lgkmcnt(0)
	s_barrier
; template <int DKH, int DVW>
; __device__ __forceinline__ void gla_chain(const Params& p, int jl, unsigned char* lds, int seq, int h, int e, int dk0, int dv0, bf16_t* OUTB, int ostride, int orow_off) {
;     ...
;                 for (int ks = 0; ks < 2; ++ks) vf[dt][ks] = *(const bf16x8*)(vTw + (dt * 16 + fr) * 144 + (ks * 32 + fq * 8) * 2);
;             f32x4 o[DT][4];
;             { bf16x8 Bs[2][4];
; #pragma unroll
;               for (int ks = 0; ks < 2; ++ks)
; #pragma unroll
;                   for (int ct = 0; ct < 4; ++ct) Bs[ks][ct] = *(const bf16x8*)(sc + (ct * 16 + fr) * 144 + (ks * 32 + fq * 8) * 2);
;               bf16x8 Sbf[KS][DT];
; #pragma unroll
;               for (int ks = 0; ks < KS; ++ks)
; #pragma unroll
;                   for (int dt = 0; dt < DT; ++dt) { const f32x4 x0 = Sacc[2 * ks][dt], x1 = Sacc[2 * ks + 1][dt];
;                       const u32x4 w = (u32x4){pk2(x0[0], x0[1]), pk2(x0[2], x0[3]), pk2(x1[0], x1[1]), pk2(x1[2], x1[3])}; Sbf[ks][dt] = __builtin_bit_cast(bf16x8, w); }
;               u32x4 Bq[2][4];
;     ...
;               GLA_LDQ(0, 0);
;               __builtin_amdgcn_sched_barrier(0);
; #pragma unroll
;               for (int ct = 0; ct < 4; ++ct)
; #pragma unroll
;                   for (int dt = 0; dt < DT; ++dt) o[dt][ct] = __builtin_amdgcn_mfma_f32_16x16x32_bf16(vf[dt][0], Bs[0][ct], (f32x4){0.f, 0.f, 0.f, 0.f}, 0, 0, 0);
; #pragma unroll
;               for (int ct = 0; ct < 4; ++ct)
; #pragma unroll
;                   for (int dt = 0; dt < DT; ++dt) o[dt][ct] = __builtin_amdgcn_mfma_f32_16x16x32_bf16(vf[dt][1], Bs[1][ct], o[dt][ct], 0, 0, 0);
; #pragma unroll
;               for (int ks = 0; ks < KS; ++ks) {
;                   if (ks < KS - 1) GLA_LDQ((ks + 1) & 1, ks + 1);
;                   __builtin_amdgcn_sched_barrier(0);
; #pragma unroll
;                   for (int ct = 0; ct < 4; ++ct) { const bf16x8 B = __builtin_bit_cast(bf16x8, Bq[ks & 1][ct]);
; #pragma unroll
;                       for (int dt = 0; dt < DT; ++dt) o[dt][ct] = __builtin_amdgcn_mfma_f32_16x16x32_bf16(Sbf[ks][dt], B, o[dt][ct], 0, 0, 0); }
;                   __builtin_amdgcn_sched_barrier(0);
;               }
;     ...
;             }
; #pragma unroll
;             for (int ct = 0; ct < 4; ++ct)
; #pragma unroll
;                 for (int dt = 0; dt < DT; ++dt) { u32x2 w; w.x = pk2(o[dt][ct][0], o[dt][ct][1]); w.y = pk2(o[dt][ct][2], o[dt][ct][3]);
	ds_read_b128 v[22:25], v98
	ds_read_b128 v[26:29], v98 offset:64
	ds_read_b128 v[30:33], v34
	ds_read_b128 v[34:37], v34 offset:64
	ds_read_b128 v[38:41], v58
	ds_read_b128 v[42:45], v58 offset:64
	ds_read_b128 v[46:49], v58 offset:2304
	ds_read_b128 v[50:53], v58 offset:2368
	ds_read_b128 v[54:57], v58 offset:4608
	ds_read_b128 v[58:61], v58 offset:4672
	ds_read2_b64 v[74:77], v78 offset0:128 offset1:132
	ds_read2_b64 v[102:105], v79 offset0:160 offset1:164
	ds_read2_b64 v[106:109], v118 offset0:192 offset1:196
	ds_read2_b64 v[110:113], v119 offset0:224 offset1:228
	v_cvt_pk_bf16_f32 v114, v14, v15
	v_cvt_pk_bf16_f32 v115, v16, v17
	v_cvt_pk_bf16_f32 v116, v18, v19
	v_cvt_pk_bf16_f32 v117, v20, v21
	s_waitcnt lgkmcnt(11)
	v_mfma_f32_16x16x32_bf16 v[30:33], v[22:25], v[30:33], 0
	s_waitcnt lgkmcnt(9)
	v_mfma_f32_16x16x32_bf16 v[38:41], v[22:25], v[38:41], 0
	s_waitcnt lgkmcnt(7)
	v_mfma_f32_16x16x32_bf16 v[46:49], v[22:25], v[46:49], 0
	s_waitcnt lgkmcnt(5)
	v_mfma_f32_16x16x32_bf16 v[54:57], v[22:25], v[54:57], 0
	v_mfma_f32_16x16x32_bf16 v[30:33], v[26:29], v[34:37], v[30:33]
	v_mfma_f32_16x16x32_bf16 v[34:37], v[26:29], v[42:45], v[38:41]
	v_mfma_f32_16x16x32_bf16 v[38:41], v[26:29], v[50:53], v[46:49]
	s_waitcnt lgkmcnt(4)
	v_mfma_f32_16x16x32_bf16 v[42:45], v[26:29], v[58:61], v[54:57]
	s_nop 0
	ds_read2_b64 v[46:49], v78 offset0:136 offset1:140
	ds_read2_b64 v[50:53], v79 offset0:168 offset1:172
	ds_read2_b64 v[54:57], v118 offset0:200 offset1:204
	ds_read2_b64 v[58:61], v119 offset0:232 offset1:236
	s_waitcnt lgkmcnt(7)
	v_mfma_f32_16x16x32_bf16 v[30:33], v[70:73], v[74:77], v[30:33]
	s_waitcnt lgkmcnt(6)
	v_mfma_f32_16x16x32_bf16 v[34:37], v[70:73], v[102:105], v[34:37]
	s_waitcnt lgkmcnt(5)
	v_mfma_f32_16x16x32_bf16 v[38:41], v[70:73], v[106:109], v[38:41]
	s_waitcnt lgkmcnt(4)
	v_mfma_f32_16x16x32_bf16 v[42:45], v[70:73], v[110:113], v[42:45]
	s_waitcnt lgkmcnt(3)
	v_mfma_f32_16x16x32_bf16 v[30:33], v[114:117], v[46:49], v[30:33]
	s_waitcnt lgkmcnt(2)
	v_mfma_f32_16x16x32_bf16 v[34:37], v[114:117], v[50:53], v[34:37]
	s_waitcnt lgkmcnt(1)
	v_mfma_f32_16x16x32_bf16 v[38:41], v[114:117], v[54:57], v[38:41]
	s_waitcnt lgkmcnt(0)
	v_mfma_f32_16x16x32_bf16 v[42:45], v[114:117], v[58:61], v[42:45]
	v_add_u32_e32 v46, s96, v90
	v_ashrrev_i32_e32 v47, 31, v46
	v_cvt_pk_bf16_f32 v30, v30, v31
	v_cvt_pk_bf16_f32 v31, v32, v33
	v_lshlrev_b64 v[32:33], s34, v[46:47]
	v_lshl_add_u64 v[32:33], v[32:33], 1, v[68:69]
	global_store_dwordx2 v[32:33], v[30:31], off
	v_or_b32_e32 v32, 16, v46
	v_ashrrev_i32_e32 v33, 31, v32
	v_lshlrev_b64 v[32:33], s34, v[32:33]
	v_cvt_pk_bf16_f32 v30, v34, v35
	v_cvt_pk_bf16_f32 v31, v36, v37
	v_lshl_add_u64 v[32:33], v[32:33], 1, v[68:69]
	global_store_dwordx2 v[32:33], v[30:31], off
	v_or_b32_e32 v32, 32, v46
	v_ashrrev_i32_e32 v33, 31, v32
	v_lshlrev_b64 v[32:33], s34, v[32:33]
	v_cvt_pk_bf16_f32 v30, v38, v39
	v_cvt_pk_bf16_f32 v31, v40, v41
	v_lshl_add_u64 v[32:33], v[32:33], 1, v[68:69]
	global_store_dwordx2 v[32:33], v[30:31], off
	v_or_b32_e32 v32, 48, v46
	v_ashrrev_i32_e32 v33, 31, v32
	v_lshlrev_b64 v[32:33], s34, v[32:33]
	v_cvt_pk_bf16_f32 v30, v42, v43
	v_cvt_pk_bf16_f32 v31, v44, v45
	v_lshl_add_u64 v[32:33], v[32:33], 1, v[68:69]
	global_store_dwordx2 v[32:33], v[30:31], off
	v_add_u32_e32 v74, v89, v0
	v_add_u32_e32 v38, v91, v87
	v_add_u32_e32 v78, v91, v93
	ds_read_b128 v[30:33], v74 offset:12288
	ds_read_b128 v[34:37], v38 offset:48128
	ds_read_b128 v[38:41], v38 offset:48192
	ds_read_b128 v[42:45], v74 offset:12352
	ds_read_b128 v[46:49], v78 offset:48128
	ds_read_b128 v[50:53], v78 offset:48192
	ds_read_b128 v[54:57], v74 offset:12416
	ds_read_b128 v[58:61], v78 offset:50432
	ds_read_b128 v[70:73], v78 offset:50496
	ds_read_b128 v[74:77], v74 offset:12480
	ds_read_b128 v[102:105], v78 offset:52736
	ds_read_b128 v[106:109], v78 offset:52800
	s_waitcnt lgkmcnt(11)
	v_pk_mul_f32 v[6:7], v[6:7], v[30:31]
	v_pk_mul_f32 v[8:9], v[8:9], v[32:33]
	s_waitcnt lgkmcnt(8)
	v_pk_mul_f32 v[10:11], v[10:11], v[42:43]
	v_pk_mul_f32 v[12:13], v[12:13], v[44:45]
	v_mfma_f32_16x16x32_bf16 v[6:9], v[34:37], v[22:25], v[6:9]
	s_waitcnt lgkmcnt(7)
	v_mfma_f32_16x16x32_bf16 v[10:13], v[46:49], v[22:25], v[10:13]
	v_mfma_f32_16x16x32_bf16 v[6:9], v[38:41], v[26:29], v[6:9]
	s_waitcnt lgkmcnt(6)
	v_mfma_f32_16x16x32_bf16 v[10:13], v[50:53], v[26:29], v[10:13]
	s_waitcnt lgkmcnt(5)
	v_pk_mul_f32 v[14:15], v[14:15], v[54:55]
	v_pk_mul_f32 v[16:17], v[16:17], v[56:57]
	s_waitcnt lgkmcnt(2)
	v_pk_mul_f32 v[18:19], v[18:19], v[74:75]
	v_pk_mul_f32 v[20:21], v[20:21], v[76:77]
	v_mfma_f32_16x16x32_bf16 v[14:17], v[58:61], v[22:25], v[14:17]
	s_waitcnt lgkmcnt(1)
	v_mfma_f32_16x16x32_bf16 v[18:21], v[102:105], v[22:25], v[18:21]
	v_mfma_f32_16x16x32_bf16 v[14:17], v[70:73], v[26:29], v[14:17]
	s_waitcnt lgkmcnt(0)
	v_mfma_f32_16x16x32_bf16 v[18:21], v[106:109], v[26:29], v[18:21]
	s_and_saveexec_b64 s[90:91], s[2:3]
	s_cbranch_execz .LBB0_339
	s_and_b32 s2, s35, 0x400
	v_lshl_add_u32 v22, s2, 2, v92
	ds_write_b128 v22, v[2:5]
	s_branch .LBB0_339
